# GEMM units: the second wave half takes its stagger-restoring barrier after the next-unit table lookup and pointer setup instead of before them
# baseline (speedup 1.0000x reference)
; #define PG8_STAGE(bufoff, gbase, voff) do { _Pragma("unroll") for (int _i = 0; _i < 2; ++_i) \
;         __builtin_amdgcn_global_load_lds((const unsigned*)((const char*)(gbase) + (voff)[_i]), (LAS unsigned*)(lds + (bufoff) + ldsw + _i * 8192), 16, 0, 0); } while (0)
; #define PG8_LDA(dst, b, h) do { _Pragma("unroll") for (int m = 0; m < 4; ++m) _Pragma("unroll") for (int k = 0; k < 2; ++k) dst[m][k] = *(const LAS bf16x8*)(lds + PG8_SA(b, h) + aoff + m * 2048 + k * 1024); } while (0)
; #define PG8_LDB(dst, b, h) do { _Pragma("unroll") for (int n = 0; n < 2; ++n) _Pragma("unroll") for (int k = 0; k < 2; ++k) dst[n][k] = *(const LAS bf16x8*)(lds + PG8_SB(b, h) + boff + n * 2048 + k * 1024); } while (0)
; #define PG8_MMA(ai, bj, At, Bt) do { __builtin_amdgcn_s_setprio(1); _Pragma("unroll") for (int m = 0; m < 4; ++m) _Pragma("unroll") for (int n = 0; n < 2; ++n) _Pragma("unroll") for (int k = 0; k < 2; ++k) \
;         acc[ai][bj][m][n] = __builtin_amdgcn_mfma_f32_16x16x32_bf16(Bt[n][k], At[m][k], acc[ai][bj][m][n], 0, 0, 0); __builtin_amdgcn_s_setprio(0); } while (0)
; #define PG8_WAIT_V(n) asm volatile("s_waitcnt vmcnt(" #n ")" ::: "memory")
; template <class Epi>
; __device__ __forceinline__ void gemm_phase(LAS unsigned char* lds, const Gemm g, const TabSched& S, const Epi& E) {
;     ...
;         const bool has_next = S.next(ui + 1, nxt);
;         const char* nA = has_next ? nxt.A : cA; const char* nB = has_next ? nxt.B : cB;
;         const int nt = cur.nt;
;         for (int t = 0; t < nt; t += 2) {
;             const bool last = (t == nt - 2);
;             const char* a1 = cA + (size_t)(t + 1) * kstep;
;             const char* a2 = last ? nA : cA + (size_t)(t + 2) * kstep; const char* b2 = last ? nB : cB + (size_t)(t + 2) * kstep;
;             const char* a3 = a2 + kstep; const char* b3 = b2 + kstep;
;             PG8_LDB(B0, 0, 0); PG8_LDB(B1, 0, 1); PG8_SCHED; PG8_LDA(At, 0, 0); PG8_STAGE(PG8_SA(1, 1), a1 + hstep, voffA);
;             PG8_WAIT_V(8); PG8_WAIT_L(0); PG8_BAR; PG8_MMA(0, 0, At, B0); PG8_MMA(0, 1, At, B1); PG8_BAR; PG8_SCHED;
;             PG8_LDA(At, 0, 1); PG8_STAGE(PG8_SB(0, 0), b2, voffB); PG8_STAGE(PG8_SB(0, 1), b2 + hstep, voffB); PG8_STAGE(PG8_SA(0, 0), a2, voffA);
;             PG8_WAIT_V(8); PG8_WAIT_L(0); PG8_BAR; PG8_MMA(1, 0, At, B0); PG8_MMA(1, 1, At, B1); PG8_BAR; PG8_SCHED;
;     ...
;         if (wr == 1) PG8_BAR;
.LBB0_415:
	s_cmp_lt_i32 s13, 1
	s_cbranch_scc1 .LBB0_425
	s_and_b64 s[42:43], s[44:45], exec
	s_cselect_b32 s19, s9, s27
	s_cselect_b32 s42, s8, s26
	s_cselect_b32 s43, s11, s41
	s_cselect_b32 s46, s10, s40
	s_add_i32 s47, s13, -2
	s_add_u32 s48, s40, 0x100
	s_addc_u32 s49, s41, 0
	s_add_u32 s26, s26, 0x80
	s_addc_u32 s27, s27, 0
	s_mov_b32 s40, 0
	s_cmp_lt_u32 s62, 2
	s_cbranch_scc1 .Lrb_skip
	s_andn2_b64 vcc, exec, s[4:5]
	s_cbranch_vccnz .Lrb_skip
	s_barrier
.Lrb_skip:
	s_add_i32 s50, s40, 2
	s_add_u32 s51, s26, 0x80
	s_addc_u32 s41, s27, 0
	s_add_i32 s74, 0, 0x10000
	s_cmp_eq_u32 s47, s40
	s_cselect_b32 s41, s19, s41
	s_cselect_b32 s40, s42, s51
	s_cselect_b32 s73, s43, s49
	s_cselect_b32 s72, s46, s48
	s_add_i32 s51, 0, 0x14000
	v_add_u32_e32 v166, s74, v178
	v_add_u32_e32 v188, s51, v178
	ds_read_b128 v[136:139], v166
	ds_read_b128 v[140:143], v166 offset:1024
	ds_read_b128 v[162:165], v166 offset:2048
	ds_read_b128 v[166:169], v166 offset:3072
	ds_read_b128 v[170:173], v188
	ds_read_b128 v[174:177], v188 offset:1024
	ds_read_b128 v[184:187], v188 offset:2048
	ds_read_b128 v[188:191], v188 offset:3072
	s_add_u32 s76, s26, s36
	s_addc_u32 s77, s27, 0
	s_add_i32 m0, s54, 0xc000
	ds_read_b128 v[192:195], v183
	ds_read_b128 v[196:199], v183 offset:1024
	ds_read_b128 v[200:203], v183 offset:2048
	ds_read_b128 v[204:207], v183 offset:3072
	ds_read_b128 v[208:211], v183 offset:4096
	ds_read_b128 v[230:233], v183 offset:5120
	ds_read_b128 v[234:237], v183 offset:6144
	ds_read_b128 v[238:241], v183 offset:7168
	global_load_lds_dwordx4 v2, s[76:77]
	s_add_i32 m0, s54, 0xe000
	s_nop 0
	global_load_lds_dwordx4 v146, s[76:77]
	s_waitcnt vmcnt(8)
	s_waitcnt lgkmcnt(0)
	s_barrier
	s_setprio 1
	s_waitcnt lgkmcnt(0)
	v_mfma_f32_16x16x32_bf16 v[132:135], v[136:139], v[192:195], 0
	v_mfma_f32_16x16x32_bf16 v[128:131], v[162:165], v[192:195], 0
	v_mfma_f32_16x16x32_bf16 v[124:127], v[136:139], v[200:203], 0
	v_mfma_f32_16x16x32_bf16 v[120:123], v[162:165], v[200:203], 0
	v_mfma_f32_16x16x32_bf16 v[116:119], v[136:139], v[208:211], 0
	v_mfma_f32_16x16x32_bf16 v[112:115], v[162:165], v[208:211], 0
	v_mfma_f32_16x16x32_bf16 v[108:111], v[136:139], v[234:237], 0
	v_mfma_f32_16x16x32_bf16 v[104:107], v[162:165], v[234:237], 0
	v_mfma_f32_16x16x32_bf16 v[132:135], v[140:143], v[196:199], v[132:135]
	v_mfma_f32_16x16x32_bf16 v[128:131], v[166:169], v[196:199], v[128:131]
	v_mfma_f32_16x16x32_bf16 v[124:127], v[140:143], v[204:207], v[124:127]
	v_mfma_f32_16x16x32_bf16 v[120:123], v[166:169], v[204:207], v[120:123]
	v_mfma_f32_16x16x32_bf16 v[116:119], v[140:143], v[230:233], v[116:119]
	v_mfma_f32_16x16x32_bf16 v[112:115], v[166:169], v[230:233], v[112:115]
	v_mfma_f32_16x16x32_bf16 v[108:111], v[140:143], v[238:241], v[108:111]
	v_mfma_f32_16x16x32_bf16 v[104:107], v[166:169], v[238:241], v[104:107]
	s_setprio 0
	s_setprio 1
	v_mfma_f32_16x16x32_bf16 v[100:103], v[170:173], v[192:195], 0
	v_mfma_f32_16x16x32_bf16 v[96:99], v[184:187], v[192:195], 0
	v_mfma_f32_16x16x32_bf16 v[92:95], v[170:173], v[200:203], 0
	v_mfma_f32_16x16x32_bf16 v[88:91], v[184:187], v[200:203], 0
	v_mfma_f32_16x16x32_bf16 v[84:87], v[170:173], v[208:211], 0
	v_mfma_f32_16x16x32_bf16 v[80:83], v[184:187], v[208:211], 0
	v_mfma_f32_16x16x32_bf16 v[76:79], v[170:173], v[234:237], 0
	v_mfma_f32_16x16x32_bf16 v[72:75], v[184:187], v[234:237], 0
	v_mfma_f32_16x16x32_bf16 v[100:103], v[174:177], v[196:199], v[100:103]
	v_mfma_f32_16x16x32_bf16 v[96:99], v[188:191], v[196:199], v[96:99]
	v_mfma_f32_16x16x32_bf16 v[92:95], v[174:177], v[204:207], v[92:95]
	v_mfma_f32_16x16x32_bf16 v[88:91], v[188:191], v[204:207], v[88:91]
	v_mfma_f32_16x16x32_bf16 v[84:87], v[174:177], v[230:233], v[84:87]
	v_mfma_f32_16x16x32_bf16 v[80:83], v[188:191], v[230:233], v[80:83]
	v_mfma_f32_16x16x32_bf16 v[76:79], v[174:177], v[238:241], v[76:79]
	v_mfma_f32_16x16x32_bf16 v[72:75], v[188:191], v[238:241], v[72:75]
	s_setprio 0
	s_barrier
	s_add_i32 s74, s74, s53
	s_mov_b32 m0, s74
	s_mov_b32 s78, s72
	s_mov_b32 s79, s73
	ds_read_b128 v[192:195], v183 offset:16384
	ds_read_b128 v[196:199], v183 offset:17408
	ds_read_b128 v[200:203], v183 offset:18432
	ds_read_b128 v[204:207], v183 offset:19456
	ds_read_b128 v[208:211], v183 offset:20480
	ds_read_b128 v[230:233], v183 offset:21504
	ds_read_b128 v[234:237], v183 offset:22528
	ds_read_b128 v[238:241], v183 offset:23552
	global_load_lds_dwordx4 v144, s[72:73]
	s_add_i32 m0, s74, 0x2000
	s_add_u32 s72, s72, s36
	s_addc_u32 s73, s73, 0
	s_add_i32 s51, s51, s53
	global_load_lds_dwordx4 v148, s[78:79]
	s_mov_b32 m0, s51
	s_mov_b32 s82, s72
	s_mov_b32 s83, s73
	global_load_lds_dwordx4 v144, s[72:73]
	s_add_i32 m0, s51, 0x2000
	s_mov_b32 s80, s40
	s_mov_b32 s81, s41
	global_load_lds_dwordx4 v148, s[72:73]
	s_mov_b32 m0, s54
	s_nop 0
	global_load_lds_dwordx4 v2, s[40:41]
	s_mov_b32 m0, s55
	s_nop 0
	global_load_lds_dwordx4 v146, s[40:41]
	s_waitcnt vmcnt(8)
	s_waitcnt lgkmcnt(0)
	s_barrier
; #define PG8_STAGE(bufoff, gbase, voff) do { _Pragma("unroll") for (int _i = 0; _i < 2; ++_i) \
;         __builtin_amdgcn_global_load_lds((const unsigned*)((const char*)(gbase) + (voff)[_i]), (LAS unsigned*)(lds + (bufoff) + ldsw + _i * 8192), 16, 0, 0); } while (0)
; #define PG8_LDA(dst, b, h) do { _Pragma("unroll") for (int m = 0; m < 4; ++m) _Pragma("unroll") for (int k = 0; k < 2; ++k) dst[m][k] = *(const LAS bf16x8*)(lds + PG8_SA(b, h) + aoff + m * 2048 + k * 1024); } while (0)
; #define PG8_LDB(dst, b, h) do { _Pragma("unroll") for (int n = 0; n < 2; ++n) _Pragma("unroll") for (int k = 0; k < 2; ++k) dst[n][k] = *(const LAS bf16x8*)(lds + PG8_SB(b, h) + boff + n * 2048 + k * 1024); } while (0)
; #define PG8_MMA(ai, bj, At, Bt) do { __builtin_amdgcn_s_setprio(1); _Pragma("unroll") for (int m = 0; m < 4; ++m) _Pragma("unroll") for (int n = 0; n < 2; ++n) _Pragma("unroll") for (int k = 0; k < 2; ++k) \
;         acc[ai][bj][m][n] = __builtin_amdgcn_mfma_f32_16x16x32_bf16(Bt[n][k], At[m][k], acc[ai][bj][m][n], 0, 0, 0); __builtin_amdgcn_s_setprio(0); } while (0)
; #define PG8_WAIT_V(n) asm volatile("s_waitcnt vmcnt(" #n ")" ::: "memory")
; #define PG8_WAIT_L(n) asm volatile("s_waitcnt lgkmcnt(" #n ")" ::: "memory")
; #define PG8_BAR __builtin_amdgcn_s_barrier()
; #define PG8_SCHED __builtin_amdgcn_sched_barrier(0)
; template <class Epi>
; __device__ __forceinline__ void gemm_phase(LAS unsigned char* lds, const Gemm g, const TabSched& S, const Epi& E) {
;     ...
;             PG8_WAIT_V(8); PG8_WAIT_L(0); PG8_BAR; PG8_MMA(1, 0, At, B0); PG8_MMA(1, 1, At, B1); PG8_BAR; PG8_SCHED;
;             PG8_LDB(B0, 1, 0); PG8_LDB(B1, 1, 1); PG8_SCHED; PG8_LDA(At, 1, 0); PG8_STAGE(PG8_SA(0, 1), a2 + hstep, voffA);
;             PG8_WAIT_V(8); PG8_WAIT_L(0); PG8_BAR; PG8_MMA(0, 0, At, B0); PG8_MMA(0, 1, At, B1); PG8_BAR; PG8_SCHED;
	s_setprio 1
	s_waitcnt lgkmcnt(0)
	v_mfma_f32_16x16x32_bf16 v[68:71], v[136:139], v[192:195], 0
	v_mfma_f32_16x16x32_bf16 v[64:67], v[162:165], v[192:195], 0
	v_mfma_f32_16x16x32_bf16 v[60:63], v[136:139], v[200:203], 0
	v_mfma_f32_16x16x32_bf16 v[56:59], v[162:165], v[200:203], 0
	v_mfma_f32_16x16x32_bf16 v[52:55], v[136:139], v[208:211], 0
	v_mfma_f32_16x16x32_bf16 v[48:51], v[162:165], v[208:211], 0
	v_mfma_f32_16x16x32_bf16 v[44:47], v[136:139], v[234:237], 0
	v_mfma_f32_16x16x32_bf16 v[40:43], v[162:165], v[234:237], 0
	v_mfma_f32_16x16x32_bf16 v[68:71], v[140:143], v[196:199], v[68:71]
	v_mfma_f32_16x16x32_bf16 v[64:67], v[166:169], v[196:199], v[64:67]
	v_mfma_f32_16x16x32_bf16 v[60:63], v[140:143], v[204:207], v[60:63]
	v_mfma_f32_16x16x32_bf16 v[56:59], v[166:169], v[204:207], v[56:59]
	v_mfma_f32_16x16x32_bf16 v[52:55], v[140:143], v[230:233], v[52:55]
	v_mfma_f32_16x16x32_bf16 v[48:51], v[166:169], v[230:233], v[48:51]
	v_mfma_f32_16x16x32_bf16 v[44:47], v[140:143], v[238:241], v[44:47]
	v_mfma_f32_16x16x32_bf16 v[40:43], v[166:169], v[238:241], v[40:43]
	s_setprio 0
	s_setprio 1
	v_mfma_f32_16x16x32_bf16 v[36:39], v[170:173], v[192:195], 0
	v_mfma_f32_16x16x32_bf16 v[32:35], v[184:187], v[192:195], 0
	v_mfma_f32_16x16x32_bf16 v[28:31], v[170:173], v[200:203], 0
	v_mfma_f32_16x16x32_bf16 v[24:27], v[184:187], v[200:203], 0
	v_mfma_f32_16x16x32_bf16 v[20:23], v[170:173], v[208:211], 0
	v_mfma_f32_16x16x32_bf16 v[16:19], v[184:187], v[208:211], 0
	v_mfma_f32_16x16x32_bf16 v[12:15], v[170:173], v[234:237], 0
	v_mfma_f32_16x16x32_bf16 v[8:11], v[184:187], v[234:237], 0
	v_mfma_f32_16x16x32_bf16 v[36:39], v[174:177], v[196:199], v[36:39]
	v_mfma_f32_16x16x32_bf16 v[32:35], v[188:191], v[196:199], v[32:35]
	v_mfma_f32_16x16x32_bf16 v[28:31], v[174:177], v[204:207], v[28:31]
	v_mfma_f32_16x16x32_bf16 v[24:27], v[188:191], v[204:207], v[24:27]
	v_mfma_f32_16x16x32_bf16 v[20:23], v[174:177], v[230:233], v[20:23]
	v_mfma_f32_16x16x32_bf16 v[16:19], v[188:191], v[230:233], v[16:19]
	v_mfma_f32_16x16x32_bf16 v[12:15], v[174:177], v[238:241], v[12:15]
	v_mfma_f32_16x16x32_bf16 v[8:11], v[188:191], v[238:241], v[8:11]
	s_setprio 0
	s_barrier
	s_add_i32 s51, 0, 0x18000
	s_add_i32 s72, 0, 0x1c000
	v_add_u32_e32 v166, s51, v178
	v_add_u32_e32 v188, s72, v178
	ds_read_b128 v[136:139], v166
	ds_read_b128 v[140:143], v166 offset:1024
	ds_read_b128 v[162:165], v166 offset:2048
	ds_read_b128 v[166:169], v166 offset:3072
	ds_read_b128 v[170:173], v188
	ds_read_b128 v[174:177], v188 offset:1024
	ds_read_b128 v[184:187], v188 offset:2048
	ds_read_b128 v[188:191], v188 offset:3072
	s_add_u32 s40, s40, s36
	s_addc_u32 s41, s41, 0
	s_mov_b32 m0, s56
	ds_read_b128 v[192:195], v183 offset:32768
	ds_read_b128 v[196:199], v183 offset:33792
	ds_read_b128 v[200:203], v183 offset:34816
	ds_read_b128 v[204:207], v183 offset:35840
	ds_read_b128 v[208:211], v183 offset:36864
	ds_read_b128 v[230:233], v183 offset:37888
	ds_read_b128 v[234:237], v183 offset:38912
	ds_read_b128 v[238:241], v183 offset:39936
	global_load_lds_dwordx4 v2, s[40:41]
	s_mov_b32 m0, s57
	s_nop 0
	global_load_lds_dwordx4 v146, s[40:41]
	s_waitcnt vmcnt(8)
	s_waitcnt lgkmcnt(0)
	s_barrier
	s_setprio 1
	s_waitcnt lgkmcnt(0)
	v_mfma_f32_16x16x32_bf16 v[132:135], v[136:139], v[192:195], v[132:135]
	v_mfma_f32_16x16x32_bf16 v[128:131], v[162:165], v[192:195], v[128:131]
	v_mfma_f32_16x16x32_bf16 v[124:127], v[136:139], v[200:203], v[124:127]
	v_mfma_f32_16x16x32_bf16 v[120:123], v[162:165], v[200:203], v[120:123]
	v_mfma_f32_16x16x32_bf16 v[116:119], v[136:139], v[208:211], v[116:119]
	v_mfma_f32_16x16x32_bf16 v[112:115], v[162:165], v[208:211], v[112:115]
	v_mfma_f32_16x16x32_bf16 v[108:111], v[136:139], v[234:237], v[108:111]
	v_mfma_f32_16x16x32_bf16 v[104:107], v[162:165], v[234:237], v[104:107]
	v_mfma_f32_16x16x32_bf16 v[132:135], v[140:143], v[196:199], v[132:135]
	v_mfma_f32_16x16x32_bf16 v[128:131], v[166:169], v[196:199], v[128:131]
	v_mfma_f32_16x16x32_bf16 v[124:127], v[140:143], v[204:207], v[124:127]
	v_mfma_f32_16x16x32_bf16 v[120:123], v[166:169], v[204:207], v[120:123]
	v_mfma_f32_16x16x32_bf16 v[116:119], v[140:143], v[230:233], v[116:119]
	v_mfma_f32_16x16x32_bf16 v[112:115], v[166:169], v[230:233], v[112:115]
	v_mfma_f32_16x16x32_bf16 v[108:111], v[140:143], v[238:241], v[108:111]
	v_mfma_f32_16x16x32_bf16 v[104:107], v[166:169], v[238:241], v[104:107]
	s_setprio 0
	s_setprio 1
	v_mfma_f32_16x16x32_bf16 v[100:103], v[170:173], v[192:195], v[100:103]
	v_mfma_f32_16x16x32_bf16 v[96:99], v[184:187], v[192:195], v[96:99]
	v_mfma_f32_16x16x32_bf16 v[92:95], v[170:173], v[200:203], v[92:95]
	v_mfma_f32_16x16x32_bf16 v[88:91], v[184:187], v[200:203], v[88:91]
	v_mfma_f32_16x16x32_bf16 v[84:87], v[170:173], v[208:211], v[84:87]
	v_mfma_f32_16x16x32_bf16 v[80:83], v[184:187], v[208:211], v[80:83]
	v_mfma_f32_16x16x32_bf16 v[76:79], v[170:173], v[234:237], v[76:79]
	v_mfma_f32_16x16x32_bf16 v[72:75], v[184:187], v[234:237], v[72:75]
	v_mfma_f32_16x16x32_bf16 v[100:103], v[174:177], v[196:199], v[100:103]
	v_mfma_f32_16x16x32_bf16 v[96:99], v[188:191], v[196:199], v[96:99]
	v_mfma_f32_16x16x32_bf16 v[92:95], v[174:177], v[204:207], v[92:95]
	v_mfma_f32_16x16x32_bf16 v[88:91], v[188:191], v[204:207], v[88:91]
	v_mfma_f32_16x16x32_bf16 v[84:87], v[174:177], v[230:233], v[84:87]
	v_mfma_f32_16x16x32_bf16 v[80:83], v[188:191], v[230:233], v[80:83]
	v_mfma_f32_16x16x32_bf16 v[76:79], v[174:177], v[238:241], v[76:79]
	v_mfma_f32_16x16x32_bf16 v[72:75], v[188:191], v[238:241], v[72:75]
	s_setprio 0
	s_barrier
; #define PG8_STAGE(bufoff, gbase, voff) do { _Pragma("unroll") for (int _i = 0; _i < 2; ++_i) \
;         __builtin_amdgcn_global_load_lds((const unsigned*)((const char*)(gbase) + (voff)[_i]), (LAS unsigned*)(lds + (bufoff) + ldsw + _i * 8192), 16, 0, 0); } while (0)
; #define PG8_LDA(dst, b, h) do { _Pragma("unroll") for (int m = 0; m < 4; ++m) _Pragma("unroll") for (int k = 0; k < 2; ++k) dst[m][k] = *(const LAS bf16x8*)(lds + PG8_SA(b, h) + aoff + m * 2048 + k * 1024); } while (0)
; #define PG8_MMA(ai, bj, At, Bt) do { __builtin_amdgcn_s_setprio(1); _Pragma("unroll") for (int m = 0; m < 4; ++m) _Pragma("unroll") for (int n = 0; n < 2; ++n) _Pragma("unroll") for (int k = 0; k < 2; ++k) \
;         acc[ai][bj][m][n] = __builtin_amdgcn_mfma_f32_16x16x32_bf16(Bt[n][k], At[m][k], acc[ai][bj][m][n], 0, 0, 0); __builtin_amdgcn_s_setprio(0); } while (0)
; #define PG8_WAIT_V(n) asm volatile("s_waitcnt vmcnt(" #n ")" ::: "memory")
; #define PG8_WAIT_L(n) asm volatile("s_waitcnt lgkmcnt(" #n ")" ::: "memory")
; #define PG8_BAR __builtin_amdgcn_s_barrier()
; #define PG8_SCHED __builtin_amdgcn_sched_barrier(0)
; template <class Epi>
; __device__ __forceinline__ void gemm_phase(LAS unsigned char* lds, const Gemm g, const TabSched& S, const Epi& E) {
;     ...
;         for (int t = 0; t < nt; t += 2) {
;     ...
;             PG8_LDA(At, 1, 1); PG8_STAGE(PG8_SB(1, 0), b3, voffB); PG8_STAGE(PG8_SB(1, 1), b3 + hstep, voffB); PG8_STAGE(PG8_SA(1, 0), a3, voffA);
;             PG8_WAIT_V(8); PG8_WAIT_L(0); PG8_BAR; PG8_MMA(1, 0, At, B0); PG8_MMA(1, 1, At, B1); PG8_BAR; PG8_SCHED;
;         }
	s_add_i32 s40, s51, s53
	s_add_i32 m0, s40, 0xffffff80
	ds_read_b128 v[192:195], v183 offset:49152
	ds_read_b128 v[196:199], v183 offset:50176
	ds_read_b128 v[200:203], v183 offset:51200
	ds_read_b128 v[204:207], v183 offset:52224
	ds_read_b128 v[208:211], v183 offset:53248
	ds_read_b128 v[230:233], v183 offset:54272
	ds_read_b128 v[234:237], v183 offset:55296
	ds_read_b128 v[238:241], v183 offset:56320
	global_load_lds_dwordx4 v144, s[78:79] offset:128
	s_add_i32 m0, s40, 0x1f80
	s_add_i32 s40, s72, s53
	global_load_lds_dwordx4 v148, s[78:79] offset:128
	s_add_i32 m0, s40, 0xffffff80
	s_nop 0
	global_load_lds_dwordx4 v144, s[82:83] offset:128
	s_add_i32 m0, s40, 0x1f80
	s_nop 0
	global_load_lds_dwordx4 v148, s[82:83] offset:128
	s_add_i32 m0, s58, 0xffffff80
	s_nop 0
	global_load_lds_dwordx4 v2, s[80:81] offset:128
	s_add_i32 m0, s59, 0xffffff80
	s_nop 0
	global_load_lds_dwordx4 v146, s[80:81] offset:128
	s_waitcnt vmcnt(8)
	s_waitcnt lgkmcnt(0)
	s_barrier
	s_setprio 1
	s_waitcnt lgkmcnt(0)
	v_mfma_f32_16x16x32_bf16 v[68:71], v[136:139], v[192:195], v[68:71]
	v_mfma_f32_16x16x32_bf16 v[64:67], v[162:165], v[192:195], v[64:67]
	v_mfma_f32_16x16x32_bf16 v[60:63], v[136:139], v[200:203], v[60:63]
	v_mfma_f32_16x16x32_bf16 v[56:59], v[162:165], v[200:203], v[56:59]
	v_mfma_f32_16x16x32_bf16 v[52:55], v[136:139], v[208:211], v[52:55]
	v_mfma_f32_16x16x32_bf16 v[48:51], v[162:165], v[208:211], v[48:51]
	v_mfma_f32_16x16x32_bf16 v[44:47], v[136:139], v[234:237], v[44:47]
	v_mfma_f32_16x16x32_bf16 v[40:43], v[162:165], v[234:237], v[40:43]
	v_mfma_f32_16x16x32_bf16 v[68:71], v[140:143], v[196:199], v[68:71]
	v_mfma_f32_16x16x32_bf16 v[64:67], v[166:169], v[196:199], v[64:67]
	v_mfma_f32_16x16x32_bf16 v[60:63], v[140:143], v[204:207], v[60:63]
	v_mfma_f32_16x16x32_bf16 v[56:59], v[166:169], v[204:207], v[56:59]
	v_mfma_f32_16x16x32_bf16 v[52:55], v[140:143], v[230:233], v[52:55]
	v_mfma_f32_16x16x32_bf16 v[48:51], v[166:169], v[230:233], v[48:51]
	v_mfma_f32_16x16x32_bf16 v[44:47], v[140:143], v[238:241], v[44:47]
	v_mfma_f32_16x16x32_bf16 v[40:43], v[166:169], v[238:241], v[40:43]
	s_setprio 0
	s_setprio 1
	v_mfma_f32_16x16x32_bf16 v[36:39], v[170:173], v[192:195], v[36:39]
	v_mfma_f32_16x16x32_bf16 v[32:35], v[184:187], v[192:195], v[32:35]
	v_mfma_f32_16x16x32_bf16 v[28:31], v[170:173], v[200:203], v[28:31]
	v_mfma_f32_16x16x32_bf16 v[24:27], v[184:187], v[200:203], v[24:27]
	v_mfma_f32_16x16x32_bf16 v[20:23], v[170:173], v[208:211], v[20:23]
	v_mfma_f32_16x16x32_bf16 v[16:19], v[184:187], v[208:211], v[16:19]
	v_mfma_f32_16x16x32_bf16 v[12:15], v[170:173], v[234:237], v[12:15]
	v_mfma_f32_16x16x32_bf16 v[8:11], v[184:187], v[234:237], v[8:11]
	v_mfma_f32_16x16x32_bf16 v[36:39], v[174:177], v[196:199], v[36:39]
	v_mfma_f32_16x16x32_bf16 v[32:35], v[188:191], v[196:199], v[32:35]
	v_mfma_f32_16x16x32_bf16 v[28:31], v[174:177], v[204:207], v[28:31]
	v_mfma_f32_16x16x32_bf16 v[24:27], v[188:191], v[204:207], v[24:27]
	v_mfma_f32_16x16x32_bf16 v[20:23], v[174:177], v[230:233], v[20:23]
	v_mfma_f32_16x16x32_bf16 v[16:19], v[188:191], v[230:233], v[16:19]
	v_mfma_f32_16x16x32_bf16 v[12:15], v[174:177], v[238:241], v[12:15]
	v_mfma_f32_16x16x32_bf16 v[8:11], v[188:191], v[238:241], v[8:11]
	s_setprio 0
	s_barrier
	s_add_u32 s48, s48, 0x100
	s_addc_u32 s49, s49, 0
	s_add_u32 s26, s26, 0x100
	s_addc_u32 s27, s27, 0
	s_cmp_ge_i32 s50, s13
	s_mov_b32 s40, s50
	s_cbranch_scc1 .Lk1_exit
